# chunkB: previous-token rows taken from neighbouring lanes via DPP, only fr==0 lanes load them
# speedup vs baseline: 1.0422x; 1.0097x over previous
; __device__ __forceinline__ void chunkB_item(const Args& A, LAS unsigned char* lds, int tid, int lane, int wave, int bh) {
;     ...
;     B_LOAD(p0, q0, 0); B_LOADY(r0_, ya0, zc0, zp0, zg0, bc0, 0);
.LBB0_275:
	s_or_b64 exec, exec, s[12:13]
	v_mov_b32_e32 v0, s34
	s_waitcnt lgkmcnt(0)
	s_barrier
	ds_read_b32 v0, v0
	s_movk_i32 s13, 0x7f
	s_mov_b64 s[14:15], -1
	s_waitcnt lgkmcnt(0)
	s_barrier
	v_cmp_lt_i32_e32 vcc, s13, v0
	v_readfirstlane_b32 s12, v0
	s_cbranch_vccnz .LBB0_270
	s_mov_b32 s100, 0x10001
	s_mov_b32 s101, 0x10001
	s_and_b32 s38, s12, 7
	s_ashr_i32 s13, s12, 31
	s_mul_i32 s14, s12, 0xc0000
	s_mul_hi_i32 s15, s12, 0xc0000
	s_add_u32 s14, s86, s14
	s_addc_u32 s15, s87, s15
	s_add_u32 s16, s14, 0x2000
	v_lshlrev_b32_e32 v94, 8, v91
	v_lshl_add_u32 v94, v132, 4, v94
	s_addc_u32 s17, s15, 0
	v_lshl_add_u64 v[8:9], s[14:15], 0, v[94:95]
	v_mov_b32_e32 v125, v95
	v_mov_b32_e32 v127, v95
	v_lshl_add_u64 v[4:5], v[8:9], 0, v[124:125]
	v_lshl_add_u64 v[10:11], v[98:99], 2, s[16:17]
	v_lshl_add_u64 v[12:13], v[100:101], 2, s[16:17]
	v_lshl_add_u64 v[14:15], v[102:103], 2, s[16:17]
	v_lshl_add_u64 v[8:9], v[8:9], 0, v[126:127]
	global_load_dwordx4 v[0:3], v[4:5], off
	s_nop 0
	global_load_dwordx4 v[4:7], v[4:5], off offset:1024
	v_lshl_add_u64 v[16:17], v[104:105], 2, s[16:17]
	global_load_dword v210, v[10:11], off
	global_load_dword v211, v[12:13], off
	global_load_dword v212, v[14:15], off
	global_load_dword v213, v[16:17], off
	global_load_dwordx4 v[36:39], v[8:9], off
	global_load_dwordx4 v[20:23], v[8:9], off offset:1024
	v_lshl_add_u64 v[8:9], v[108:109], 2, s[16:17]
	v_lshl_add_u64 v[10:11], v[110:111], 2, s[16:17]
	v_lshl_add_u64 v[12:13], v[112:113], 2, s[16:17]
	v_lshl_add_u64 v[14:15], v[114:115], 2, s[16:17]
	s_ashr_i32 s14, s12, 3
	s_lshl_b64 s[16:17], s[12:13], 19
	s_add_u32 s18, s3, s16
	s_addc_u32 s19, s11, s17
	v_mov_b32_e32 v149, v95
	global_load_dword v40, v[8:9], off
	global_load_dword v41, v[10:11], off
	global_load_dword v42, v[12:13], off
	global_load_dword v43, v[14:15], off
	v_lshl_add_u64 v[8:9], s[18:19], 0, v[148:149]
	s_ashr_i32 s15, s14, 31
	v_lshl_add_u64 v[16:17], s[18:19], 0, v[94:95]
	v_lshl_add_u64 v[18:19], v[8:9], 0, s[8:9]
	s_lshl_b64 s[16:17], s[14:15], 11
	v_lshl_add_u64 v[12:13], v[16:17], 0, v[124:125]
	v_lshl_add_u64 v[24:25], v[18:19], 0, v[124:125]
	global_load_dwordx4 v[8:11], v[12:13], off
	s_nop 0
	global_load_dwordx4 v[12:15], v[12:13], off offset:1024
	v_or_b32_e32 v27, s16, v96
	global_load_dwordx2 v[196:197], v[24:25], off
	v_mov_b64_e32 v[24:25], s[94:95]
	v_lshl_add_u32 v26, s38, 6, v92
	v_mad_u64_u32 v[24:25], s[18:19], v27, s35, v[24:25]
	v_mad_i32_i24 v25, s17, v147, v25
	v_lshlrev_b32_e32 v150, 1, v26
	v_mov_b32_e32 v151, v95
	v_lshl_add_u64 v[24:25], v[24:25], 0, v[150:151]
	global_load_dwordx2 v[174:175], v[24:25], off offset:2048
	v_mov_b32_e32 v170, v95
	v_mov_b32_e32 v171, v95
	s_and_saveexec_b64 s[18:19], s[4:5]
	s_cbranch_execz .LBB0_278
	v_add_co_u32_e32 v28, vcc, 0xfffff000, v24
	s_nop 1
	v_addc_co_u32_e32 v29, vcc, -1, v25, vcc
	global_load_dwordx2 v[170:171], v[28:29], off offset:-1024

; __device__ __forceinline__ void chunkB_item(const Args& A, LAS unsigned char* lds, int tid, int lane, int wave, int bh) {
;     ...
;         for (int nn = 0; nn < 2; ++nn) { p0[nn][0] = p1[nn][0]; p0[nn][1] = p1[nn][1]; q0[nn] = q1[nn]; r0_[nn][0] = r1_[nn][0]; r0_[nn][1] = r1_[nn][1];
;             ya0[nn] = ya1[nn]; zc0[nn] = zc1[nn]; zp0[nn] = zp1[nn]; zg0[nn] = zg1[nn]; bc0[nn] = bc1[nn]; }
.LBB0_279:
	s_or_b64 exec, exec, s[22:23]
	s_waitcnt lgkmcnt(0)
	s_barrier
	ds_read2st64_b64 v[20:23], v141 offset0:36 offset1:37
	s_waitcnt lgkmcnt(1)
	ds_read2st64_b64 v[36:39], v141 offset0:38 offset1:39
	v_lshlrev_b32_e32 v42, 16, v176
	v_and_b32_e32 v43, 0xffff0000, v176
	v_lshlrev_b32_e32 v40, 16, v174
	s_waitcnt lgkmcnt(1)
	v_pk_add_f32 v[20:21], v[20:21], 0 op_sel_hi:[1,0]
	v_and_b32_e32 v41, 0xffff0000, v174
	v_pk_add_f32 v[20:21], v[20:21], v[22:23]
	v_mul_f32_e32 v23, 0xbfb8aa3b, v42
	s_waitcnt lgkmcnt(0)
	v_pk_add_f32 v[20:21], v[20:21], v[36:37]
	v_exp_f32_e32 v23, v23
	v_pk_add_f32 v[20:21], v[20:21], v[38:39]
	v_lshlrev_b32_e32 v36, 16, v170
	v_pk_mul_f32 v[20:21], v[20:21], s[10:11] op_sel_hi:[1,0]
	v_add_f32_e32 v23, 1.0, v23
	v_fma_f32 v22, -v20, v20, v21
	v_max_f32_e32 v22, 0, v22
	v_add_f32_e32 v22, 0x3a27c5ac, v22
	v_rcp_f32_e32 v38, v23
	v_mul_f32_e32 v23, 0xbfb8aa3b, v43
	v_rsq_f32_e32 v22, v22
	v_exp_f32_e32 v23, v23
	v_and_b32_e32 v37, 0xffff0000, v170
	v_pk_add_f32 v[56:57], v[198:199], v[20:21] op_sel_hi:[1,0] neg_lo:[0,1] neg_hi:[0,1]
	v_pk_add_f32 v[36:37], v[36:37], v[40:41] neg_lo:[0,1] neg_hi:[0,1]
	v_pk_mul_f32 v[56:57], v[56:57], v[22:23] op_sel_hi:[1,0]
	v_add_f32_e32 v23, 1.0, v23
	s_waitcnt vmcnt(0)
	v_pk_fma_f32 v[36:37], v[36:37], v[60:61], v[40:41]
	v_lshlrev_b32_e32 v40, 16, v177
	v_rcp_f32_e32 v39, v23
	v_mul_f32_e32 v23, 0xbfb8aa3b, v40
	v_exp_f32_e32 v23, v23
	v_pk_fma_f32 v[56:57], v[64:65], v[56:57], v[68:69]
	v_and_b32_e32 v41, 0xffff0000, v177
	v_pk_fma_f32 v[36:37], v[172:173], v[36:37], v[56:57] op_sel_hi:[0,1,1]
	v_add_f32_e32 v23, 1.0, v23
	v_rcp_f32_e32 v56, v23
	v_mul_f32_e32 v23, 0xbfb8aa3b, v41
	v_exp_f32_e32 v23, v23
	v_pk_add_f32 v[20:21], v[196:197], v[20:21] op_sel_hi:[1,0] neg_lo:[0,1] neg_hi:[0,1]
	v_pk_mul_f32 v[38:39], v[38:39], v[42:43]
	v_lshlrev_b32_e32 v42, 16, v171
	v_pk_mul_f32 v[20:21], v[20:21], v[22:23] op_sel_hi:[1,0]
	v_add_f32_e32 v22, 1.0, v23
	v_rcp_f32_e32 v57, v22
	v_pk_mul_f32 v[36:37], v[38:39], v[36:37]
	v_lshlrev_b32_e32 v38, 16, v175
	v_and_b32_e32 v39, 0xffff0000, v175
	v_and_b32_e32 v43, 0xffff0000, v171
	v_pk_add_f32 v[22:23], v[42:43], v[38:39] neg_lo:[0,1] neg_hi:[0,1]
	v_pk_fma_f32 v[20:21], v[66:67], v[20:21], v[70:71]
	v_pk_fma_f32 v[22:23], v[22:23], v[62:63], v[38:39]
	v_lshl_add_u64 v[42:43], v[160:161], 0, s[20:21]
	v_pk_fma_f32 v[20:21], v[172:173], v[22:23], v[20:21] op_sel_hi:[0,1,1]
	v_pk_mul_f32 v[22:23], v[56:57], v[40:41]
	v_cvt_pk_bf16_f32 v40, v36, v37
	v_pk_mul_f32 v[38:39], v[22:23], v[20:21]
	ds_read2st64_b64 v[20:23], v143 offset0:36 offset1:37
	v_cvt_pk_bf16_f32 v41, v38, v39
	ds_read2st64_b64 v[36:39], v143 offset0:38 offset1:39
	global_store_dwordx2 v[42:43], v[40:41], off
	v_lshlrev_b32_e32 v40, 16, v164
	s_waitcnt lgkmcnt(1)
	v_pk_add_f32 v[20:21], v[20:21], 0 op_sel_hi:[1,0]
	v_and_b32_e32 v41, 0xffff0000, v164
	v_pk_add_f32 v[20:21], v[20:21], v[22:23]
	v_mov_b64_e32 v[58:59], v[46:47]
	s_waitcnt lgkmcnt(0)
	v_pk_add_f32 v[20:21], v[20:21], v[36:37]
	v_lshlrev_b32_e32 v36, 16, v168
	v_pk_add_f32 v[20:21], v[20:21], v[38:39]
	v_lshlrev_b32_e32 v38, 16, v166
	v_mul_f32_e32 v23, 0xbfb8aa3b, v38
	v_exp_f32_e32 v23, v23
	v_pk_mul_f32 v[20:21], v[20:21], s[10:11] op_sel_hi:[1,0]
	v_and_b32_e32 v39, 0xffff0000, v166
	v_fma_f32 v22, -v20, v20, v21
	v_max_f32_e32 v22, 0, v22
	v_add_f32_e32 v23, 1.0, v23
	v_add_f32_e32 v22, 0x3a27c5ac, v22
	v_rcp_f32_e32 v42, v23
	v_mul_f32_e32 v23, 0xbfb8aa3b, v39
	v_rsq_f32_e32 v22, v22
	v_exp_f32_e32 v23, v23
	v_and_b32_e32 v37, 0xffff0000, v168
	v_pk_add_f32 v[54:55], v[54:55], v[20:21] op_sel_hi:[1,0] neg_lo:[0,1] neg_hi:[0,1]
	v_pk_add_f32 v[40:41], v[40:41], v[36:37] neg_lo:[0,1] neg_hi:[0,1]
	v_pk_mul_f32 v[54:55], v[54:55], v[22:23] op_sel_hi:[1,0]
	v_add_f32_e32 v23, 1.0, v23
	v_pk_fma_f32 v[36:37], v[40:41], v[60:61], v[36:37]
	v_lshlrev_b32_e32 v40, 16, v167
	v_rcp_f32_e32 v43, v23
	v_mul_f32_e32 v23, 0xbfb8aa3b, v40
	v_exp_f32_e32 v23, v23
	v_pk_fma_f32 v[54:55], v[64:65], v[54:55], v[68:69]
	v_and_b32_e32 v41, 0xffff0000, v167
	v_pk_fma_f32 v[36:37], v[162:163], v[36:37], v[54:55] op_sel_hi:[0,1,1]
	v_add_f32_e32 v23, 1.0, v23
	v_rcp_f32_e32 v54, v23
	v_mul_f32_e32 v23, 0xbfb8aa3b, v41
	v_exp_f32_e32 v23, v23
	v_pk_add_f32 v[20:21], v[52:53], v[20:21] op_sel_hi:[1,0] neg_lo:[0,1] neg_hi:[0,1]
	v_pk_mul_f32 v[38:39], v[42:43], v[38:39]
	v_lshlrev_b32_e32 v42, 16, v165
	v_pk_mul_f32 v[20:21], v[20:21], v[22:23] op_sel_hi:[1,0]
	v_add_f32_e32 v22, 1.0, v23
	v_rcp_f32_e32 v55, v22
	v_pk_mul_f32 v[36:37], v[38:39], v[36:37]
	v_lshlrev_b32_e32 v38, 16, v169
	v_and_b32_e32 v39, 0xffff0000, v169
	v_and_b32_e32 v43, 0xffff0000, v165
	v_pk_add_f32 v[22:23], v[42:43], v[38:39] neg_lo:[0,1] neg_hi:[0,1]
	v_pk_fma_f32 v[20:21], v[66:67], v[20:21], v[70:71]
	v_pk_fma_f32 v[22:23], v[22:23], v[62:63], v[38:39]
	v_mov_b32_dpp v192, v182 row_ror:1 row_mask:0xf bank_mask:0xf
	v_mov_b32_dpp v193, v183 row_ror:1 row_mask:0xf bank_mask:0xf
	v_mov_b32_dpp v192, v188 row_shr:1 row_mask:0xf bank_mask:0xf
	v_mov_b32_dpp v193, v189 row_shr:1 row_mask:0xf bank_mask:0xf
	v_mov_b64_e32 v[164:165], v[192:193]
	v_pk_fma_f32 v[20:21], v[162:163], v[22:23], v[20:21] op_sel_hi:[0,1,1]
	v_pk_mul_f32 v[22:23], v[54:55], v[40:41]
	v_mov_b64_e32 v[54:55], v[50:51]
	v_pk_mul_f32 v[20:21], v[22:23], v[20:21]
	v_cvt_pk_bf16_f32 v22, v36, v37
	v_cvt_pk_bf16_f32 v23, v20, v21
	v_lshl_add_u64 v[20:21], v[158:159], 0, s[20:21]
	s_add_u32 s20, s20, 0x20000
	global_store_dwordx2 v[20:21], v[22:23], off
	s_addc_u32 s21, s21, 0
	s_add_i32 s39, s39, 1
	v_mov_b64_e32 v[38:39], v[26:27]
	v_mov_b64_e32 v[20:21], v[28:29]
	s_cmp_eq_u32 s20, 0x400000
	v_mov_b32_dpp v186, v182 row_shr:1 row_mask:0xf bank_mask:0xf
	v_mov_b32_dpp v187, v183 row_shr:1 row_mask:0xf bank_mask:0xf
	v_mov_b64_e32 v[170:171], v[186:187]
	v_mov_b64_e32 v[166:167], v[190:191]
	v_mov_b64_e32 v[176:177], v[184:185]
	v_mov_b64_e32 v[174:175], v[182:183]
	v_mov_b64_e32 v[168:169], v[188:189]
	v_mov_b32_e32 v162, v127
	v_mov_b32_e32 v172, v125
	v_mov_b64_e32 v[56:57], v[44:45]
	v_mov_b64_e32 v[52:53], v[48:49]
	v_mov_b64_e32 v[36:37], v[24:25]
	v_mov_b64_e32 v[22:23], v[30:31]
	v_mov_b32_e32 v40, v216
	v_mov_b32_e32 v41, v217
	v_mov_b32_e32 v42, v218
	v_mov_b32_e32 v43, v219
	v_mov_b32_e32 v196, v178
	v_mov_b32_e32 v197, v179
	v_mov_b32_e32 v194, v180
	v_mov_b32_e32 v195, v181
	s_cbranch_scc1 .LBB0_268
.LBB0_280:
	s_cmp_lg_u32 s20, 0x3e0000
	s_cselect_b32 s15, s39, 31
	s_add_u32 s22, s18, s15
	s_addc_u32 s23, s19, 0
	s_mul_i32 s40, s23, 0x6000
	s_mul_hi_u32 s41, s22, 0x6000
	s_add_i32 s41, s41, s40
	s_mul_i32 s40, s22, 0x6000
	s_add_u32 s40, s86, s40
	s_addc_u32 s41, s87, s41
	s_waitcnt vmcnt(12)
	v_mov_b64_e32 v[226:227], v[10:11]
	s_add_u32 s42, s40, 0x2000
	v_mov_b64_e32 v[224:225], v[8:9]
	s_addc_u32 s43, s41, 0
	v_lshl_add_u64 v[8:9], s[40:41], 0, v[94:95]
	s_lshl_b64 s[40:41], s[22:23], 14
	s_add_u32 s40, s3, s40
	s_addc_u32 s41, s11, s41
	s_lshl_b64 s[22:23], s[22:23], 8
	s_add_u32 s22, s24, s22
	v_mov_b64_e32 v[74:75], v[6:7]
	v_mov_b32_e32 v125, v95
	v_mov_b32_e32 v127, v95
	s_addc_u32 s23, s25, s23
	s_lshl_b32 s15, s15, 6
	v_mov_b64_e32 v[72:73], v[4:5]
	v_mov_b64_e32 v[200:201], v[2:3]
	s_waitcnt vmcnt(11)
	v_mov_b64_e32 v[222:223], v[14:15]
	v_lshl_add_u64 v[4:5], v[8:9], 0, v[124:125]
	v_lshl_add_u64 v[10:11], v[98:99], 2, s[42:43]
	v_lshl_add_u64 v[24:25], v[104:105], 2, s[42:43]
	v_lshl_add_u64 v[8:9], v[8:9], 0, v[126:127]
	s_add_u32 s15, s16, s15
	v_mov_b64_e32 v[198:199], v[0:1]
	v_mov_b64_e32 v[220:221], v[12:13]
	v_mov_b32_e32 v76, v210
	v_mov_b32_e32 v77, v211
	v_mov_b32_e32 v78, v212
	v_mov_b32_e32 v79, v213
	global_load_dwordx4 v[0:3], v[4:5], off
	s_nop 0
	global_load_dwordx4 v[4:7], v[4:5], off offset:1024
	v_lshl_add_u64 v[12:13], v[100:101], 2, s[42:43]
	v_lshl_add_u64 v[14:15], v[102:103], 2, s[42:43]
	global_load_dword v210, v[10:11], off
	global_load_dword v211, v[12:13], off
	global_load_dword v212, v[14:15], off
	global_load_dword v213, v[24:25], off
	s_nop 0
	global_load_dwordx4 v[24:27], v[8:9], off
	global_load_dwordx4 v[28:31], v[8:9], off offset:1024
	v_lshl_add_u64 v[8:9], v[108:109], 2, s[42:43]
	v_mov_b32_e32 v149, v95
	v_or_b32_e32 v48, s15, v96
	v_mov_b64_e32 v[62:63], s[94:95]
	v_lshl_add_u64 v[10:11], v[110:111], 2, s[42:43]
	v_lshl_add_u64 v[12:13], v[112:113], 2, s[42:43]
	v_lshl_add_u64 v[14:15], v[114:115], 2, s[42:43]
	global_load_dword v216, v[8:9], off
	global_load_dword v217, v[10:11], off
	global_load_dword v218, v[12:13], off
	global_load_dword v219, v[14:15], off
	s_addc_u32 s42, s17, 0
	v_lshl_add_u64 v[44:45], s[40:41], 0, v[94:95]
	v_lshl_add_u64 v[8:9], s[40:41], 0, v[148:149]
	v_mad_u64_u32 v[48:49], s[40:41], v48, s35, v[62:63]
	v_mad_i32_i24 v49, s42, v147, v49
	v_mov_b32_e32 v151, v95
	v_or_b32_e32 v64, s15, v106
	v_lshl_add_u64 v[48:49], v[48:49], 0, v[150:151]
	v_mad_u64_u32 v[62:63], s[40:41], v64, s35, v[62:63]
	v_add_co_u32_e32 v50, vcc, s36, v48
	v_mad_i32_i24 v63, s42, v147, v63
	v_lshl_add_u64 v[60:61], v[8:9], 0, s[8:9]
	v_addc_co_u32_e32 v51, vcc, -1, v49, vcc
	v_lshl_add_u64 v[62:63], v[62:63], 0, v[150:151]
	v_lshl_add_u64 v[12:13], v[44:45], 0, v[124:125]
	v_lshl_add_u64 v[46:47], v[60:61], 0, v[124:125]
	v_add_co_u32_e32 v64, vcc, s36, v62
	global_load_dwordx4 v[8:11], v[12:13], off
	s_nop 0
	global_load_dwordx4 v[12:15], v[12:13], off offset:1024
	s_nop 0
	global_load_dwordx2 v[178:179], v[46:47], off
	global_load_dwordx2 v[182:183], v[48:49], off offset:2048
	s_mov_b64 exec, s[100:101]
	global_load_dwordx2 v[186:187], v[50:51], off offset:-1024
	s_mov_b64 exec, -1
	global_load_dwordx2 v[184:185], v[48:49], off offset:3328
	v_lshl_add_u64 v[48:49], v[44:45], 0, v[126:127]
	v_lshl_add_u64 v[60:61], v[60:61], 0, v[126:127]
	v_addc_co_u32_e32 v65, vcc, -1, v63, vcc
	global_load_dwordx4 v[44:47], v[48:49], off
	s_nop 0
	global_load_dwordx4 v[48:51], v[48:49], off offset:1024
	s_nop 0
	global_load_dwordx2 v[180:181], v[60:61], off
	global_load_dwordx2 v[188:189], v[62:63], off offset:2048
	s_mov_b64 exec, s[100:101]
	global_load_dwordx2 v[192:193], v[64:65], off offset:-1024
	s_mov_b64 exec, -1
	global_load_dwordx2 v[190:191], v[62:63], off offset:3328
	global_load_dword v125, v214, s[22:23]
	global_load_dword v127, v215, s[22:23]
	s_nop 0
	global_load_dwordx4 v[64:67], v[152:153], off
	global_load_dwordx4 v[68:71], v[154:155], off
	global_load_dwordx4 v[60:63], v[156:157], off
	v_cvt_pk_bf16_f32 v80, v16, 0
	v_lshlrev_b32_e32 v81, 16, v80
	v_sub_f32_e32 v16, v16, v81
	v_cvt_pk_bf16_f32 v16, v16, s0
	ds_write_b16 v107, v80
	ds_write_b16 v107, v16 offset:9216
	v_cvt_pk_bf16_f32 v16, v17, 0
	v_lshlrev_b32_e32 v80, 16, v16
	v_sub_f32_e32 v17, v17, v80
	v_cvt_pk_bf16_f32 v17, v17, s0
	ds_write_b16 v107, v16 offset:144
	ds_write_b16 v107, v17 offset:9360
	v_cvt_pk_bf16_f32 v16, v18, 0
	v_lshlrev_b32_e32 v17, 16, v16
	v_sub_f32_e32 v17, v18, v17
	v_cvt_pk_bf16_f32 v17, v17, s0
	ds_write_b16 v107, v16 offset:288
	ds_write_b16 v107, v17 offset:9504
	v_cvt_pk_bf16_f32 v16, v19, 0
	v_lshlrev_b32_e32 v17, 16, v16
	v_sub_f32_e32 v17, v19, v17
	v_cvt_pk_bf16_f32 v17, v17, s0
	ds_write_b16 v107, v16 offset:432
	ds_write_b16 v107, v17 offset:9648
	v_cvt_pk_bf16_f32 v16, v32, 0
	v_lshlrev_b32_e32 v17, 16, v16
	v_sub_f32_e32 v17, v32, v17
	v_cvt_pk_bf16_f32 v17, v17, s0
	ds_write_b16 v135, v16
	ds_write_b16 v135, v17 offset:9216
	v_cvt_pk_bf16_f32 v16, v33, 0
	v_lshlrev_b32_e32 v17, 16, v16
	v_sub_f32_e32 v17, v33, v17
	v_cvt_pk_bf16_f32 v17, v17, s0
	ds_write_b16 v135, v16 offset:144
	ds_write_b16 v135, v17 offset:9360
	v_cvt_pk_bf16_f32 v16, v34, 0
	v_lshlrev_b32_e32 v17, 16, v16
	v_sub_f32_e32 v17, v34, v17
	v_cvt_pk_bf16_f32 v17, v17, s0
	ds_write_b16 v135, v16 offset:288
	ds_write_b16 v135, v17 offset:9504
	v_cvt_pk_bf16_f32 v16, v35, 0
	v_lshlrev_b32_e32 v17, 16, v16
	v_sub_f32_e32 v17, v35, v17
	v_cvt_pk_bf16_f32 v17, v17, s0
	ds_write_b16 v135, v16 offset:432
	ds_write_b16 v135, v17 offset:9648
	s_waitcnt lgkmcnt(0)
	s_barrier
	ds_read_b128 v[80:83], v139
	ds_read_b128 v[32:35], v139 offset:64
	s_waitcnt lgkmcnt(1)
	v_mfma_f32_16x16x32_bf16 v[16:19], v[80:83], v[198:201], v[76:79]
	ds_read_b128 v[84:87], v139 offset:9216
	s_nop 1
	ds_read_b128 v[76:79], v139 offset:9280
	s_waitcnt vmcnt(39)
	v_lshlrev_b32_e32 v202, 16, v196
	v_and_b32_e32 v203, 0xffff0000, v196
	s_waitcnt lgkmcnt(1)
	v_mfma_f32_16x16x32_bf16 v[16:19], v[84:87], v[198:201], v[16:19]
	v_lshlrev_b32_e32 v196, 16, v197
	v_and_b32_e32 v197, 0xffff0000, v197
	v_and_b32_e32 v151, 64, v209
	v_mfma_f32_16x16x32_bf16 v[198:201], v[80:83], v[224:227], 0
	v_xor_b32_e32 v149, 16, v209
	v_add_u32_e32 v151, 64, v151
	v_cmp_lt_i32_e32 vcc, v149, v151
	v_mfma_f32_16x16x32_bf16 v[198:201], v[32:35], v[220:223], v[198:201]
	v_xor_b32_e32 v224, 32, v209
	v_cndmask_b32_e32 v149, v209, v149, vcc
	v_lshlrev_b32_e32 v149, 2, v149
	v_cmp_lt_i32_e32 vcc, v224, v151
	v_mfma_f32_16x16x32_bf16 v[16:19], v[32:35], v[72:75], v[16:19]
	s_nop 2
	v_add_f32_e64 v198, v198, v202
	v_add_f32_e64 v199, v199, v203
	v_pk_add_f32 v[196:197], v[200:201], v[196:197]
	v_pk_mul_f32 v[200:201], v[198:199], v[198:199]
	v_pk_mul_f32 v[202:203], v[196:197], v[196:197]
	v_mov_b32_e32 v220, v198
	v_mov_b32_e32 v221, v200
	v_mov_b32_e32 v200, v199
	v_pk_add_f32 v[200:201], v[220:221], v[200:201]
	v_mov_b32_e32 v220, v196
	v_mov_b32_e32 v221, v202
	v_mov_b32_e32 v202, v197
	v_pk_add_f32 v[202:203], v[220:221], v[202:203]
	v_cndmask_b32_e32 v151, v209, v224, vcc
	v_pk_add_f32 v[200:201], v[200:201], v[202:203]
	ds_bpermute_b32 v202, v149, v200
	ds_bpermute_b32 v203, v149, v201
	v_lshlrev_b32_e32 v151, 2, v151
	s_waitcnt lgkmcnt(2)
	v_mfma_f32_16x16x32_bf16 v[16:19], v[76:79], v[72:75], v[16:19]
	s_waitcnt lgkmcnt(0)
	v_pk_add_f32 v[200:201], v[200:201], v[202:203]
	ds_bpermute_b32 v202, v151, v200
	ds_bpermute_b32 v203, v151, v201
	s_and_saveexec_b64 s[22:23], s[30:31]
	s_cbranch_execz .LBB0_282
	s_waitcnt lgkmcnt(0)
	v_pk_add_f32 v[72:73], v[200:201], v[202:203]
	v_add_u32_e32 v74, s26, v130
	ds_write_b64 v74, v[72:73] offset:18432
